# XCD-owned token ranges through every phase after P0: residual-phase rows remapped to the producing XCD; seams 1-7 synchronise one XCD only (conv halo of an XCD range is the zero padding of a sequence
# speedup vs baseline: 1.0602x; 1.0261x over previous
.LBB0_427:
	s_andn2_saveexec_b64 s[8:9], s[8:9]
	s_cbranch_execz .LBB0_447
	s_mov_b64 s[8:9], exec
	s_cmp_eq_u32 s101, 0
	s_cbranch_scc0 .LBB0_444
	buffer_wbl2 sc1
	s_waitcnt vmcnt(0)
	v_mbcnt_lo_u32_b32 v0, s8, 0
	v_mbcnt_hi_u32_b32 v0, s9, v0
	v_cmp_eq_u32_e32 vcc, 0, v0
	s_and_saveexec_b64 s[10:11], vcc
	s_cbranch_execz .LBB0_430
	s_bcnt1_i32_b64 s8, s[8:9]
	v_mov_b32_e32 v1, 0x1403000
	v_mov_b32_e32 v2, s8
	global_atomic_add v1, v1, v2, s[60:61] offset:1024 sc0
.LBB0_430:
	s_or_b64 exec, exec, s[10:11]
	v_readlane_b32 s10, v243, 5
	s_waitcnt vmcnt(0)
	v_readfirstlane_b32 s8, v1
	s_sub_i32 s9, 0, s10
	v_cvt_f32_u32_e32 v2, s10
	v_add_u32_e32 v0, s8, v0
	v_add_u32_e32 v3, 1, v0
	s_mov_b64 s[12:13], -1
	v_rcp_iflag_f32_e32 v2, v2
	s_nop 0
	v_mul_f32_e32 v1, 0x4f7ffffe, v2
	v_cvt_u32_f32_e32 v1, v1
	v_mul_lo_u32 v2, s9, v1
	v_mul_hi_u32 v2, v1, v2
	v_add_u32_e32 v1, v1, v2
	v_mul_hi_u32 v1, v0, v1
	v_mul_lo_u32 v2, v1, s10
	v_sub_u32_e32 v0, v0, v2
	v_add_u32_e32 v4, 1, v1
	v_cmp_le_u32_e32 vcc, s10, v0
	v_subrev_u32_e32 v2, s10, v0
	s_nop 0
	v_cndmask_b32_e32 v1, v1, v4, vcc
	v_cndmask_b32_e32 v0, v0, v2, vcc
	v_add_u32_e32 v2, 1, v1
	v_cmp_le_u32_e32 vcc, s10, v0
	s_nop 1
	v_cndmask_b32_e32 v2, v1, v2, vcc
	v_mul_lo_u32 v0, s10, v2
	v_add_u32_e32 v0, s10, v0
	s_add_u32 s10, s60, 0x1403500
	s_addc_u32 s11, s61, 0
	v_cmp_ne_u32_e32 vcc, v3, v0
	v_mov_b64_e32 v[0:1], s[10:11]
	s_and_saveexec_b64 s[8:9], vcc
	s_cbranch_execz .LBB0_442
	v_mov_b32_e32 v0, 0
	global_load_dword v1, v0, s[10:11] sc1
	s_mov_b64 s[24:25], 0
	s_waitcnt vmcnt(0)
	v_cmp_eq_u32_e32 vcc, v1, v2
	s_and_saveexec_b64 s[22:23], vcc
	s_cbranch_execz .LBB0_441
	s_add_u32 s12, s60, 0x1400200
	s_addc_u32 s13, s61, 0
	s_mov_b32 s36, 1
	s_branch .LBB0_434

.LBB0_571:
	s_cmp_lt_i32 s62, 5
	s_cselect_b64 s[4:5], -1, 0
	s_and_b64 s[4:5], s[4:5], s[2:3]
	s_andn2_b64 vcc, exec, s[4:5]
	s_cbranch_vccnz .LBB0_595
	s_and_b32 s2, s33, 7
	s_lshl_b32 s2, s2, 12
	s_lshr_b32 s98, s33, 3
	s_lshl_b32 s98, s98, 3
	s_add_i32 s2, s2, s98
	s_and_b32 s98, s33, 7
	s_add_i32 s98, s98, 1
	s_lshl_b32 s98, s98, 12
	v_readlane_b32 s3, v243, 6
	s_add_i32 s12, s3, s2
	s_cmp_ge_i32 s12, s98
	s_cbranch_scc1 .LBB0_595
	v_lshlrev_b32_e32 v16, 4, v206
	global_load_dwordx4 v[0:3], v16, s[40:41]
	global_load_dwordx4 v[4:7], v16, s[40:41] offset:1024
	global_load_dwordx4 v[8:11], v16, s[40:41] offset:2048
	global_load_dwordx4 v[12:15], v16, s[40:41] offset:3072
	v_mbcnt_lo_u32_b32 v16, -1, 0
	v_mbcnt_hi_u32_b32 v16, -1, v16
	v_and_b32_e32 v17, 64, v16
	v_add_u32_e32 v17, 64, v17
	v_xor_b32_e32 v18, 1, v16
	v_cmp_lt_i32_e32 vcc, v18, v17
	s_add_u32 s28, s60, 0x1600000
	s_addc_u32 s29, s61, 0
	v_cndmask_b32_e32 v18, v16, v18, vcc
	v_lshlrev_b32_e32 v136, 2, v18
	v_xor_b32_e32 v18, 2, v16
	v_cmp_lt_i32_e32 vcc, v18, v17
	s_add_u32 s30, s60, 0x1500000
	s_addc_u32 s31, s61, 0
	v_cndmask_b32_e32 v18, v16, v18, vcc
	v_lshlrev_b32_e32 v137, 2, v18
	v_xor_b32_e32 v18, 4, v16
	v_cmp_lt_i32_e32 vcc, v18, v17
	s_movk_i32 s6, 0x100
	v_lshlrev_b32_e32 v64, 3, v206
	v_cndmask_b32_e32 v18, v16, v18, vcc
	v_lshlrev_b32_e32 v138, 2, v18
	v_xor_b32_e32 v18, 8, v16
	v_cmp_lt_i32_e32 vcc, v18, v17
	v_mov_b32_e32 v65, 0
	s_ashr_i32 s7, s6, 31
	v_cndmask_b32_e32 v18, v16, v18, vcc
	v_lshlrev_b32_e32 v139, 2, v18
	v_xor_b32_e32 v18, 16, v16
	v_cmp_lt_i32_e32 vcc, v18, v17
	v_lshl_add_u64 v[66:67], s[42:43], 0, v[64:65]
	v_lshl_add_u64 v[68:69], s[68:69], 0, v[64:65]
	v_cndmask_b32_e32 v18, v16, v18, vcc
	v_lshlrev_b32_e32 v140, 2, v18
	v_xor_b32_e32 v18, 32, v16
	v_cmp_lt_i32_e32 vcc, v18, v17
	v_lshl_add_u64 v[70:71], s[44:45], 0, v[64:65]
	v_cmp_eq_u32_e64 s[2:3], 0, v206
	v_cndmask_b32_e32 v16, v16, v18, vcc
	v_lshlrev_b32_e32 v141, 2, v16
	s_movk_i32 s34, 0x200
	s_movk_i32 s35, 0x300
	s_lshl_b64 s[8:9], s[6:7], 2
	v_mov_b32_e32 v142, 0x358637bd
	s_mov_b32 s7, 0x800000
	s_branch .LBB0_576

.LBB0_575:
	s_add_i32 s10, s10, s6
	s_add_i32 s10, s10, s6
	s_add_i32 s12, s10, s6
	s_cmp_lt_i32 s12, s98
	s_cbranch_scc0 .LBB0_595
.LBB0_576:
	s_ashr_i32 s13, s12, 31
	s_lshl_b64 s[22:23], s[12:13], 11
	s_lshl_b64 s[24:25], s[12:13], 2
	s_add_u32 s14, s28, s24
	v_lshl_add_u64 v[120:121], v[68:69], 0, s[22:23]
	s_addc_u32 s15, s29, s25
	global_load_dword v64, v65, s[14:15]
	global_load_dwordx2 v[126:127], v[120:121], off nt
	global_load_dwordx2 v[124:125], v[120:121], off offset:512 nt
	global_load_dwordx2 v[122:123], v[120:121], off offset:1024 nt
	s_nop 0
	global_load_dwordx2 v[120:121], v[120:121], off offset:1536 nt
	v_lshl_add_u64 v[128:129], v[66:67], 0, s[22:23]
	global_load_dwordx2 v[134:135], v[128:129], off nt
	global_load_dwordx2 v[132:133], v[128:129], off offset:512 nt
	global_load_dwordx2 v[130:131], v[128:129], off offset:1024 nt
	s_nop 0
	global_load_dwordx2 v[128:129], v[128:129], off offset:1536 nt
	s_add_i32 s10, s12, s6
	s_cmp_lt_i32 s10, s98
	s_cselect_b64 s[20:21], -1, 0
	s_cmp_ge_i32 s10, s98
	s_cbranch_scc1 .LBB0_578
	s_ashr_i32 s11, s10, 31
	s_lshl_b64 s[16:17], s[10:11], 11
	v_lshl_add_u64 v[40:41], v[68:69], 0, s[16:17]
	s_add_u32 s14, s14, s8
	global_load_dwordx2 v[42:43], v[40:41], off nt
	global_load_dwordx2 v[48:49], v[40:41], off offset:512 nt
	global_load_dwordx2 v[50:51], v[40:41], off offset:1024 nt
	s_nop 0
	global_load_dwordx2 v[40:41], v[40:41], off offset:1536 nt
	v_lshl_add_u64 v[56:57], v[66:67], 0, s[16:17]
	s_addc_u32 s15, s15, s9
	global_load_dwordx2 v[58:59], v[56:57], off nt
	global_load_dwordx2 v[60:61], v[56:57], off offset:512 nt
	global_load_dwordx2 v[62:63], v[56:57], off offset:1024 nt
	global_load_dwordx2 v[118:119], v[56:57], off offset:1536 nt
	global_load_dword v144, v65, s[14:15]
	s_waitcnt vmcnt(0)
	v_lshlrev_b32_e32 v56, 16, v42
	v_and_b32_e32 v57, 0xffff0000, v42
	v_lshlrev_b32_e32 v42, 16, v43
	v_and_b32_e32 v43, 0xffff0000, v43
	v_lshlrev_b32_e32 v146, 16, v48
	v_and_b32_e32 v147, 0xffff0000, v48
	v_lshlrev_b32_e32 v48, 16, v49
	v_and_b32_e32 v49, 0xffff0000, v49
	v_lshlrev_b32_e32 v148, 16, v50
	v_and_b32_e32 v149, 0xffff0000, v50
	v_lshlrev_b32_e32 v150, 16, v51
	v_and_b32_e32 v151, 0xffff0000, v51
	v_lshlrev_b32_e32 v152, 16, v40
	v_and_b32_e32 v153, 0xffff0000, v40
	v_lshlrev_b32_e32 v154, 16, v41
	v_and_b32_e32 v155, 0xffff0000, v41
	v_lshlrev_b32_e32 v94, 16, v58
	v_and_b32_e32 v95, 0xffff0000, v58
	v_lshlrev_b32_e32 v104, 16, v59
	v_and_b32_e32 v105, 0xffff0000, v59
	v_lshlrev_b32_e32 v92, 16, v60
	v_and_b32_e32 v93, 0xffff0000, v60
	v_lshlrev_b32_e32 v110, 16, v61
	v_and_b32_e32 v111, 0xffff0000, v61
	v_lshlrev_b32_e32 v90, 16, v62
	v_and_b32_e32 v91, 0xffff0000, v62
	v_lshlrev_b32_e32 v114, 16, v63
	v_and_b32_e32 v115, 0xffff0000, v63
	v_lshlrev_b32_e32 v88, 16, v118
	v_and_b32_e32 v89, 0xffff0000, v118
	v_lshlrev_b32_e32 v118, 16, v119
	v_pk_mul_f32 v[42:43], v[144:145], v[42:43] op_sel_hi:[0,1]
	v_pk_mul_f32 v[40:41], v[144:145], v[56:57] op_sel_hi:[0,1]
	v_pk_mul_f32 v[50:51], v[144:145], v[48:49] op_sel_hi:[0,1]
	v_pk_mul_f32 v[48:49], v[144:145], v[146:147] op_sel_hi:[0,1]
	v_pk_mul_f32 v[58:59], v[144:145], v[150:151] op_sel_hi:[0,1]
	v_pk_mul_f32 v[56:57], v[144:145], v[148:149] op_sel_hi:[0,1]
	v_pk_mul_f32 v[62:63], v[144:145], v[154:155] op_sel_hi:[0,1]
	v_pk_mul_f32 v[60:61], v[144:145], v[152:153] op_sel_hi:[0,1]
	v_and_b32_e32 v119, 0xffff0000, v119
.LBB0_578:
	s_add_i32 s14, s34, s12
	s_cmp_lt_i32 s14, s98
	s_cselect_b64 s[18:19], -1, 0
	s_cmp_ge_i32 s14, s98
	s_cbranch_scc1 .LBB0_580
	s_ashr_i32 s15, s14, 31
	s_lshl_b64 s[16:17], s[14:15], 11
	v_lshl_add_u64 v[32:33], v[68:69], 0, s[16:17]
	v_lshl_add_u64 v[44:45], v[66:67], 0, s[16:17]
	s_lshl_b64 s[16:17], s[14:15], 2
	s_add_u32 s16, s28, s16
	global_load_dwordx2 v[34:35], v[32:33], off nt
	global_load_dwordx2 v[36:37], v[32:33], off offset:512 nt
	global_load_dwordx2 v[38:39], v[32:33], off offset:1024 nt
	s_nop 0
	global_load_dwordx2 v[32:33], v[32:33], off offset:1536 nt
	s_addc_u32 s17, s29, s17
	global_load_dwordx2 v[46:47], v[44:45], off nt
	global_load_dwordx2 v[52:53], v[44:45], off offset:512 nt
	global_load_dwordx2 v[54:55], v[44:45], off offset:1024 nt
	global_load_dwordx2 v[116:117], v[44:45], off offset:1536 nt
	global_load_dword v144, v65, s[16:17]
	s_waitcnt vmcnt(0)
	v_lshlrev_b32_e32 v44, 16, v34
	v_and_b32_e32 v45, 0xffff0000, v34
	v_lshlrev_b32_e32 v34, 16, v35
	v_and_b32_e32 v35, 0xffff0000, v35
	v_lshlrev_b32_e32 v146, 16, v36
	v_and_b32_e32 v147, 0xffff0000, v36
	v_lshlrev_b32_e32 v36, 16, v37
	v_and_b32_e32 v37, 0xffff0000, v37
	v_lshlrev_b32_e32 v148, 16, v38
	v_and_b32_e32 v149, 0xffff0000, v38
	v_lshlrev_b32_e32 v150, 16, v39
	v_and_b32_e32 v151, 0xffff0000, v39
	v_lshlrev_b32_e32 v152, 16, v32
	v_and_b32_e32 v153, 0xffff0000, v32
	v_lshlrev_b32_e32 v154, 16, v33
	v_and_b32_e32 v155, 0xffff0000, v33
	v_lshlrev_b32_e32 v86, 16, v46
	v_and_b32_e32 v87, 0xffff0000, v46
	v_lshlrev_b32_e32 v100, 16, v47
	v_and_b32_e32 v101, 0xffff0000, v47
	v_lshlrev_b32_e32 v84, 16, v52
	v_and_b32_e32 v85, 0xffff0000, v52
	v_lshlrev_b32_e32 v106, 16, v53
	v_and_b32_e32 v107, 0xffff0000, v53
	v_lshlrev_b32_e32 v82, 16, v54
	v_and_b32_e32 v83, 0xffff0000, v54
	v_lshlrev_b32_e32 v112, 16, v55
	v_and_b32_e32 v113, 0xffff0000, v55
	v_lshlrev_b32_e32 v80, 16, v116
	v_and_b32_e32 v81, 0xffff0000, v116
	v_lshlrev_b32_e32 v116, 16, v117
	v_pk_mul_f32 v[34:35], v[144:145], v[34:35] op_sel_hi:[0,1]
	v_pk_mul_f32 v[32:33], v[144:145], v[44:45] op_sel_hi:[0,1]
	v_pk_mul_f32 v[38:39], v[144:145], v[36:37] op_sel_hi:[0,1]
	v_pk_mul_f32 v[36:37], v[144:145], v[146:147] op_sel_hi:[0,1]
	v_pk_mul_f32 v[46:47], v[144:145], v[150:151] op_sel_hi:[0,1]
	v_pk_mul_f32 v[44:45], v[144:145], v[148:149] op_sel_hi:[0,1]
	v_pk_mul_f32 v[54:55], v[144:145], v[154:155] op_sel_hi:[0,1]
	v_pk_mul_f32 v[52:53], v[144:145], v[152:153] op_sel_hi:[0,1]
	v_and_b32_e32 v117, 0xffff0000, v117
.LBB0_580:
	s_add_i32 s12, s35, s12
	s_cmp_lt_i32 s12, s98
	s_cselect_b64 s[16:17], -1, 0
	s_cmp_ge_i32 s12, s98
	s_cbranch_scc1 .LBB0_582
	s_ashr_i32 s13, s12, 31
	s_lshl_b64 s[26:27], s[12:13], 11
	v_lshl_add_u64 v[16:17], v[68:69], 0, s[26:27]
	v_lshl_add_u64 v[24:25], v[66:67], 0, s[26:27]
	s_lshl_b64 s[26:27], s[12:13], 2
	s_add_u32 s26, s28, s26
	global_load_dwordx2 v[18:19], v[16:17], off nt
	global_load_dwordx2 v[20:21], v[16:17], off offset:512 nt
	global_load_dwordx2 v[22:23], v[16:17], off offset:1024 nt
	s_nop 0
	global_load_dwordx2 v[16:17], v[16:17], off offset:1536 nt
	s_addc_u32 s27, s29, s27
	global_load_dwordx2 v[26:27], v[24:25], off nt
	global_load_dwordx2 v[28:29], v[24:25], off offset:512 nt
	global_load_dwordx2 v[30:31], v[24:25], off offset:1024 nt
	global_load_dwordx2 v[108:109], v[24:25], off offset:1536 nt
	global_load_dword v144, v65, s[26:27]
	s_waitcnt vmcnt(0)
	v_lshlrev_b32_e32 v24, 16, v18
	v_and_b32_e32 v25, 0xffff0000, v18
	v_lshlrev_b32_e32 v18, 16, v19
	v_and_b32_e32 v19, 0xffff0000, v19
	v_lshlrev_b32_e32 v146, 16, v20
	v_and_b32_e32 v147, 0xffff0000, v20
	v_lshlrev_b32_e32 v20, 16, v21
	v_and_b32_e32 v21, 0xffff0000, v21
	v_lshlrev_b32_e32 v148, 16, v22
	v_and_b32_e32 v149, 0xffff0000, v22
	v_lshlrev_b32_e32 v150, 16, v23
	v_and_b32_e32 v151, 0xffff0000, v23
	v_lshlrev_b32_e32 v152, 16, v16
	v_and_b32_e32 v153, 0xffff0000, v16
	v_lshlrev_b32_e32 v154, 16, v17
	v_and_b32_e32 v155, 0xffff0000, v17
	v_lshlrev_b32_e32 v78, 16, v26
	v_and_b32_e32 v79, 0xffff0000, v26
	v_lshlrev_b32_e32 v96, 16, v27
	v_and_b32_e32 v97, 0xffff0000, v27
	v_lshlrev_b32_e32 v76, 16, v28
	v_and_b32_e32 v77, 0xffff0000, v28
	v_lshlrev_b32_e32 v98, 16, v29
	v_and_b32_e32 v99, 0xffff0000, v29
	v_lshlrev_b32_e32 v74, 16, v30
	v_and_b32_e32 v75, 0xffff0000, v30
	v_lshlrev_b32_e32 v102, 16, v31
	v_and_b32_e32 v103, 0xffff0000, v31
	v_lshlrev_b32_e32 v72, 16, v108
	v_and_b32_e32 v73, 0xffff0000, v108
	v_lshlrev_b32_e32 v108, 16, v109
	v_pk_mul_f32 v[18:19], v[144:145], v[18:19] op_sel_hi:[0,1]
	v_pk_mul_f32 v[16:17], v[144:145], v[24:25] op_sel_hi:[0,1]
	v_pk_mul_f32 v[22:23], v[144:145], v[20:21] op_sel_hi:[0,1]
	v_pk_mul_f32 v[20:21], v[144:145], v[146:147] op_sel_hi:[0,1]
	v_pk_mul_f32 v[26:27], v[144:145], v[150:151] op_sel_hi:[0,1]
	v_pk_mul_f32 v[24:25], v[144:145], v[148:149] op_sel_hi:[0,1]
	v_pk_mul_f32 v[30:31], v[144:145], v[154:155] op_sel_hi:[0,1]
	v_pk_mul_f32 v[28:29], v[144:145], v[152:153] op_sel_hi:[0,1]
	v_and_b32_e32 v109, 0xffff0000, v109

.LBB0_913:
	s_cmp_lt_i32 s62, 9
	s_cselect_b64 s[0:1], -1, 0
	s_and_b64 s[0:1], s[0:1], s[2:3]
	s_andn2_b64 vcc, exec, s[0:1]
	s_cbranch_vccnz .LBB0_929
	s_and_b32 s0, s33, 7
	s_lshl_b32 s0, s0, 12
	s_lshr_b32 s98, s33, 3
	s_lshl_b32 s98, s98, 3
	s_add_i32 s0, s0, s98
	s_and_b32 s98, s33, 7
	s_add_i32 s98, s98, 1
	s_lshl_b32 s98, s98, 12
	v_readlane_b32 s1, v243, 6
	s_add_i32 s6, s1, s0
	s_cmp_ge_i32 s6, s98
	s_cbranch_scc1 .LBB0_929
	v_lshlrev_b32_e32 v64, 4, v206
	s_waitcnt lgkmcnt(0)
	global_load_dwordx4 v[0:3], v64, s[56:57]
	global_load_dwordx4 v[4:7], v64, s[56:57] offset:1024
	global_load_dwordx4 v[8:11], v64, s[56:57] offset:2048
	global_load_dwordx4 v[12:15], v64, s[56:57] offset:3072
	v_mov_b32_e32 v65, 0
	v_lshlrev_b32_e32 v16, 3, v206
	v_mov_b32_e32 v17, v65
	v_lshl_add_u64 v[66:67], s[42:43], 0, v[16:17]
	v_lshl_add_u64 v[68:69], s[44:45], 0, v[16:17]
	v_mbcnt_lo_u32_b32 v16, -1, 0
	v_mbcnt_hi_u32_b32 v16, -1, v16
	v_and_b32_e32 v17, 64, v16
	v_add_u32_e32 v17, 64, v17
	v_xor_b32_e32 v18, 1, v16
	v_cmp_lt_i32_e32 vcc, v18, v17
	s_add_u32 s18, s60, 0x1500000
	s_addc_u32 s19, s61, 0
	v_cndmask_b32_e32 v18, v16, v18, vcc
	v_lshlrev_b32_e32 v136, 2, v18
	v_xor_b32_e32 v18, 2, v16
	v_cmp_lt_i32_e32 vcc, v18, v17
	s_movk_i32 s0, 0x100
	s_ashr_i32 s1, s0, 31
	v_cndmask_b32_e32 v18, v16, v18, vcc
	v_lshlrev_b32_e32 v137, 2, v18
	v_xor_b32_e32 v18, 4, v16
	v_cmp_lt_i32_e32 vcc, v18, v17
	v_lshl_add_u64 v[70:71], s[58:59], 0, v[64:65]
	s_movk_i32 s20, 0x200
	v_cndmask_b32_e32 v18, v16, v18, vcc
	v_lshlrev_b32_e32 v138, 2, v18
	v_xor_b32_e32 v18, 8, v16
	v_cmp_lt_i32_e32 vcc, v18, v17
	s_movk_i32 s21, 0x300
	s_lshl_b64 s[2:3], s[0:1], 2
	v_cndmask_b32_e32 v18, v16, v18, vcc
	v_lshlrev_b32_e32 v139, 2, v18
	v_xor_b32_e32 v18, 16, v16
	v_cmp_lt_i32_e32 vcc, v18, v17
	v_mov_b32_e32 v142, 0x358637bd
	s_mov_b32 s1, 0x800000
	v_cndmask_b32_e32 v18, v16, v18, vcc
	v_lshlrev_b32_e32 v140, 2, v18
	v_xor_b32_e32 v18, 32, v16
	v_cmp_lt_i32_e32 vcc, v18, v17
	s_nop 1
	v_cndmask_b32_e32 v16, v16, v18, vcc
	v_lshlrev_b32_e32 v141, 2, v16
	s_branch .LBB0_917
.LBB0_916:
	s_add_i32 s4, s4, s0
	s_add_i32 s4, s4, s0
	s_add_i32 s6, s4, s0
	s_cmp_lt_i32 s6, s98
	s_cbranch_scc0 .LBB0_929
.LBB0_917:
	s_ashr_i32 s7, s6, 31
	s_lshl_b64 s[4:5], s[6:7], 11
	s_lshl_b64 s[8:9], s[6:7], 2
	s_add_u32 s8, s18, s8
	v_lshl_add_u64 v[120:121], v[68:69], 0, s[4:5]
	s_addc_u32 s9, s19, s9
	global_load_dword v64, v65, s[8:9]
	global_load_dwordx2 v[126:127], v[120:121], off nt
	global_load_dwordx2 v[124:125], v[120:121], off offset:512 nt
	global_load_dwordx2 v[122:123], v[120:121], off offset:1024 nt
	s_nop 0
	global_load_dwordx2 v[120:121], v[120:121], off offset:1536 nt
	v_lshl_add_u64 v[128:129], v[66:67], 0, s[4:5]
	global_load_dwordx2 v[134:135], v[128:129], off nt
	global_load_dwordx2 v[132:133], v[128:129], off offset:512 nt
	global_load_dwordx2 v[130:131], v[128:129], off offset:1024 nt
	s_nop 0
	global_load_dwordx2 v[128:129], v[128:129], off offset:1536 nt
	s_add_i32 s4, s6, s0
	s_cmp_lt_i32 s4, s98
	s_cselect_b64 s[10:11], -1, 0
	s_cmp_ge_i32 s4, s98
	s_cbranch_scc1 .LBB0_919
	s_ashr_i32 s5, s4, 31
	s_lshl_b64 s[12:13], s[4:5], 11
	v_lshl_add_u64 v[44:45], v[68:69], 0, s[12:13]
	s_add_u32 s8, s8, s2
	global_load_dwordx2 v[46:47], v[44:45], off nt
	global_load_dwordx2 v[52:53], v[44:45], off offset:512 nt
	global_load_dwordx2 v[54:55], v[44:45], off offset:1024 nt
	global_load_dwordx2 v[56:57], v[44:45], off offset:1536 nt
	v_lshl_add_u64 v[44:45], v[66:67], 0, s[12:13]
	s_addc_u32 s9, s9, s3
	global_load_dwordx2 v[58:59], v[44:45], off nt
	global_load_dwordx2 v[60:61], v[44:45], off offset:512 nt
	global_load_dwordx2 v[62:63], v[44:45], off offset:1024 nt
	global_load_dwordx2 v[118:119], v[44:45], off offset:1536 nt
	global_load_dword v144, v65, s[8:9]
	s_waitcnt vmcnt(0)
	v_lshlrev_b32_e32 v44, 16, v46
	v_and_b32_e32 v45, 0xffff0000, v46
	v_lshlrev_b32_e32 v46, 16, v47
	v_and_b32_e32 v47, 0xffff0000, v47
	v_lshlrev_b32_e32 v146, 16, v52
	v_and_b32_e32 v147, 0xffff0000, v52
	v_lshlrev_b32_e32 v52, 16, v53
	v_and_b32_e32 v53, 0xffff0000, v53
	v_lshlrev_b32_e32 v148, 16, v54
	v_and_b32_e32 v149, 0xffff0000, v54
	v_lshlrev_b32_e32 v150, 16, v55
	v_and_b32_e32 v151, 0xffff0000, v55
	v_lshlrev_b32_e32 v152, 16, v56
	v_and_b32_e32 v153, 0xffff0000, v56
	v_lshlrev_b32_e32 v154, 16, v57
	v_and_b32_e32 v155, 0xffff0000, v57
	v_lshlrev_b32_e32 v94, 16, v58
	v_and_b32_e32 v95, 0xffff0000, v58
	v_lshlrev_b32_e32 v104, 16, v59
	v_and_b32_e32 v105, 0xffff0000, v59
	v_lshlrev_b32_e32 v92, 16, v60
	v_and_b32_e32 v93, 0xffff0000, v60
	v_lshlrev_b32_e32 v110, 16, v61
	v_and_b32_e32 v111, 0xffff0000, v61
	v_lshlrev_b32_e32 v90, 16, v62
	v_and_b32_e32 v91, 0xffff0000, v62
	v_lshlrev_b32_e32 v114, 16, v63
	v_and_b32_e32 v115, 0xffff0000, v63
	v_lshlrev_b32_e32 v88, 16, v118
	v_and_b32_e32 v89, 0xffff0000, v118
	v_lshlrev_b32_e32 v118, 16, v119
	v_pk_mul_f32 v[46:47], v[144:145], v[46:47] op_sel_hi:[0,1]
	v_pk_mul_f32 v[44:45], v[144:145], v[44:45] op_sel_hi:[0,1]
	v_pk_mul_f32 v[54:55], v[144:145], v[52:53] op_sel_hi:[0,1]
	v_pk_mul_f32 v[52:53], v[144:145], v[146:147] op_sel_hi:[0,1]
	v_pk_mul_f32 v[58:59], v[144:145], v[150:151] op_sel_hi:[0,1]
	v_pk_mul_f32 v[56:57], v[144:145], v[148:149] op_sel_hi:[0,1]
	v_pk_mul_f32 v[62:63], v[144:145], v[154:155] op_sel_hi:[0,1]
	v_pk_mul_f32 v[60:61], v[144:145], v[152:153] op_sel_hi:[0,1]
	v_and_b32_e32 v119, 0xffff0000, v119
.LBB0_919:
	s_add_i32 s8, s20, s6
	s_cmp_lt_i32 s8, s98
	s_cselect_b64 s[14:15], -1, 0
	s_cmp_ge_i32 s8, s98
	s_cbranch_scc1 .LBB0_921
	s_ashr_i32 s9, s8, 31
	s_lshl_b64 s[12:13], s[8:9], 11
	v_lshl_add_u64 v[32:33], v[68:69], 0, s[12:13]
	global_load_dwordx2 v[34:35], v[32:33], off nt
	global_load_dwordx2 v[36:37], v[32:33], off offset:512 nt
	global_load_dwordx2 v[38:39], v[32:33], off offset:1024 nt
	global_load_dwordx2 v[40:41], v[32:33], off offset:1536 nt
	v_lshl_add_u64 v[32:33], v[66:67], 0, s[12:13]
	s_lshl_b64 s[12:13], s[8:9], 2
	s_add_u32 s12, s18, s12
	s_addc_u32 s13, s19, s13
	global_load_dwordx2 v[42:43], v[32:33], off nt
	global_load_dwordx2 v[48:49], v[32:33], off offset:512 nt
	global_load_dwordx2 v[50:51], v[32:33], off offset:1024 nt
	global_load_dwordx2 v[116:117], v[32:33], off offset:1536 nt
	global_load_dword v144, v65, s[12:13]
	s_waitcnt vmcnt(0)
	v_lshlrev_b32_e32 v32, 16, v34
	v_and_b32_e32 v33, 0xffff0000, v34
	v_lshlrev_b32_e32 v34, 16, v35
	v_and_b32_e32 v35, 0xffff0000, v35
	v_lshlrev_b32_e32 v146, 16, v36
	v_and_b32_e32 v147, 0xffff0000, v36
	v_lshlrev_b32_e32 v36, 16, v37
	v_and_b32_e32 v37, 0xffff0000, v37
	v_lshlrev_b32_e32 v148, 16, v38
	v_and_b32_e32 v149, 0xffff0000, v38
	v_lshlrev_b32_e32 v150, 16, v39
	v_and_b32_e32 v151, 0xffff0000, v39
	v_lshlrev_b32_e32 v152, 16, v40
	v_and_b32_e32 v153, 0xffff0000, v40
	v_lshlrev_b32_e32 v154, 16, v41
	v_and_b32_e32 v155, 0xffff0000, v41
	v_lshlrev_b32_e32 v86, 16, v42
	v_and_b32_e32 v87, 0xffff0000, v42
	v_lshlrev_b32_e32 v100, 16, v43
	v_and_b32_e32 v101, 0xffff0000, v43
	v_lshlrev_b32_e32 v84, 16, v48
	v_and_b32_e32 v85, 0xffff0000, v48
	v_lshlrev_b32_e32 v106, 16, v49
	v_and_b32_e32 v107, 0xffff0000, v49
	v_lshlrev_b32_e32 v82, 16, v50
	v_and_b32_e32 v83, 0xffff0000, v50
	v_lshlrev_b32_e32 v112, 16, v51
	v_and_b32_e32 v113, 0xffff0000, v51
	v_lshlrev_b32_e32 v80, 16, v116
	v_and_b32_e32 v81, 0xffff0000, v116
	v_lshlrev_b32_e32 v116, 16, v117
	v_pk_mul_f32 v[34:35], v[144:145], v[34:35] op_sel_hi:[0,1]
	v_pk_mul_f32 v[32:33], v[144:145], v[32:33] op_sel_hi:[0,1]
	v_pk_mul_f32 v[38:39], v[144:145], v[36:37] op_sel_hi:[0,1]
	v_pk_mul_f32 v[36:37], v[144:145], v[146:147] op_sel_hi:[0,1]
	v_pk_mul_f32 v[42:43], v[144:145], v[150:151] op_sel_hi:[0,1]
	v_pk_mul_f32 v[40:41], v[144:145], v[148:149] op_sel_hi:[0,1]
	v_pk_mul_f32 v[50:51], v[144:145], v[154:155] op_sel_hi:[0,1]
	v_pk_mul_f32 v[48:49], v[144:145], v[152:153] op_sel_hi:[0,1]
	v_and_b32_e32 v117, 0xffff0000, v117
.LBB0_921:
	s_add_i32 s12, s21, s6
	s_cmp_lt_i32 s12, s98
	s_cselect_b64 s[16:17], -1, 0
	s_cmp_ge_i32 s12, s98
	s_cbranch_scc1 .LBB0_923
	s_ashr_i32 s13, s12, 31
	s_lshl_b64 s[22:23], s[12:13], 11
	v_lshl_add_u64 v[16:17], v[68:69], 0, s[22:23]
	global_load_dwordx2 v[18:19], v[16:17], off nt
	global_load_dwordx2 v[20:21], v[16:17], off offset:512 nt
	global_load_dwordx2 v[22:23], v[16:17], off offset:1024 nt
	global_load_dwordx2 v[24:25], v[16:17], off offset:1536 nt
	v_lshl_add_u64 v[16:17], v[66:67], 0, s[22:23]
	s_lshl_b64 s[22:23], s[12:13], 2
	s_add_u32 s22, s18, s22
	s_addc_u32 s23, s19, s23
	global_load_dwordx2 v[26:27], v[16:17], off nt
	global_load_dwordx2 v[28:29], v[16:17], off offset:512 nt
	global_load_dwordx2 v[30:31], v[16:17], off offset:1024 nt
	global_load_dwordx2 v[108:109], v[16:17], off offset:1536 nt
	global_load_dword v144, v65, s[22:23]
	s_waitcnt vmcnt(0)
	v_lshlrev_b32_e32 v16, 16, v18
	v_and_b32_e32 v17, 0xffff0000, v18
	v_lshlrev_b32_e32 v18, 16, v19
	v_and_b32_e32 v19, 0xffff0000, v19
	v_lshlrev_b32_e32 v146, 16, v20
	v_and_b32_e32 v147, 0xffff0000, v20
	v_lshlrev_b32_e32 v20, 16, v21
	v_and_b32_e32 v21, 0xffff0000, v21
	v_lshlrev_b32_e32 v148, 16, v22
	v_and_b32_e32 v149, 0xffff0000, v22
	v_lshlrev_b32_e32 v150, 16, v23
	v_and_b32_e32 v151, 0xffff0000, v23
	v_lshlrev_b32_e32 v152, 16, v24
	v_and_b32_e32 v153, 0xffff0000, v24
	v_lshlrev_b32_e32 v154, 16, v25
	v_and_b32_e32 v155, 0xffff0000, v25
	v_lshlrev_b32_e32 v78, 16, v26
	v_and_b32_e32 v79, 0xffff0000, v26
	v_lshlrev_b32_e32 v96, 16, v27
	v_and_b32_e32 v97, 0xffff0000, v27
	v_lshlrev_b32_e32 v76, 16, v28
	v_and_b32_e32 v77, 0xffff0000, v28
	v_lshlrev_b32_e32 v98, 16, v29
	v_and_b32_e32 v99, 0xffff0000, v29
	v_lshlrev_b32_e32 v74, 16, v30
	v_and_b32_e32 v75, 0xffff0000, v30
	v_lshlrev_b32_e32 v102, 16, v31
	v_and_b32_e32 v103, 0xffff0000, v31
	v_lshlrev_b32_e32 v72, 16, v108
	v_and_b32_e32 v73, 0xffff0000, v108
	v_lshlrev_b32_e32 v108, 16, v109
	v_pk_mul_f32 v[18:19], v[144:145], v[18:19] op_sel_hi:[0,1]
	v_pk_mul_f32 v[16:17], v[144:145], v[16:17] op_sel_hi:[0,1]
	v_pk_mul_f32 v[22:23], v[144:145], v[20:21] op_sel_hi:[0,1]
	v_pk_mul_f32 v[20:21], v[144:145], v[146:147] op_sel_hi:[0,1]
	v_pk_mul_f32 v[26:27], v[144:145], v[150:151] op_sel_hi:[0,1]
	v_pk_mul_f32 v[24:25], v[144:145], v[148:149] op_sel_hi:[0,1]
	v_pk_mul_f32 v[30:31], v[144:145], v[154:155] op_sel_hi:[0,1]
	v_pk_mul_f32 v[28:29], v[144:145], v[152:153] op_sel_hi:[0,1]
	v_and_b32_e32 v109, 0xffff0000, v109
